# v35 + sample-scan step loop: the two accumulator chains of each dot product merged into one v_pk_fma_f32 chain, 15 v_pk_add_f32 merges per 4 steps removed (f32 summation order changes)
# speedup vs baseline: 1.0073x; 1.0073x over previous
; template <int R, int DEFY> __forceinline__
; __device__ __forceinline__ void scan_chain(const Params& p, int j, int seq_start, int len, int h, int dir, int gtid, float* lds  , bool do_steps, bool do_prep, int row_base, int nrows) {
;     ...
;         auto ldstep = [&](int s, VS& d) {
;             const float* b = cb + s * 384 + seg * ES;
; #pragma unroll
;             for (int q = 0; q < NQ; ++q) {
;                 d.kk[q] = *(const f4*)(b + q * 4); d.w[q] = *(const f4*)(b + 64 + q * 4); d.ka[q] = *(const f4*)(b + 128 + q * 4);
;                 d.kd[q] = *(const f4*)(b + 192 + q * 4); d.rr[q] = *(const f4*)(b + 256 + q * 4);
;             }
; #pragma unroll
;             for (int r = 0; r < R; ++r) d.vv[r] = cb[s * 384 + 320 + row + r];
;         };
;         auto cstep = [&](int s, const VS& d) {
;             float yo[R];
; #pragma unroll
;             for (int r = 0; r < R; ++r) {
;                 f2 sacc = {0.f, 0.f}, sacc2 = {0.f, 0.f};
; #pragma unroll
;                 for (int q = 0; q < NQ; ++q) {
;                     sacc = st2[r][2 * q] * __builtin_shufflevector(d.kk[q], d.kk[q], 0, 1) + sacc;
;                     sacc2 = st2[r][2 * q + 1] * __builtin_shufflevector(d.kk[q], d.kk[q], 2, 3) + sacc2;
;                 }
;                 sacc = sacc + sacc2;
;                 float sa = sacc.x + sacc.y;
;                 sa = red8(sa);
;                 const f2 sa2 = {sa, sa}, v2 = {d.vv[r], d.vv[r]};
;                 f2 yacc = {0.f, 0.f}, yacc2 = {0.f, 0.f};
; #pragma unroll
;                 for (int q = 0; q < NQ; ++q) {
;                     const f2 t0 = v2 * __builtin_shufflevector(d.kd[q], d.kd[q], 0, 1) - sa2 * __builtin_shufflevector(d.ka[q], d.ka[q], 0, 1);
;                     const f2 t1 = v2 * __builtin_shufflevector(d.kd[q], d.kd[q], 2, 3) - sa2 * __builtin_shufflevector(d.ka[q], d.ka[q], 2, 3);
;                     st2[r][2 * q] = st2[r][2 * q] * __builtin_shufflevector(d.w[q], d.w[q], 0, 1) + t0;
;                     st2[r][2 * q + 1] = st2[r][2 * q + 1] * __builtin_shufflevector(d.w[q], d.w[q], 2, 3) + t1;
;                     yacc = st2[r][2 * q] * __builtin_shufflevector(d.rr[q], d.rr[q], 0, 1) + yacc;
;                     yacc2 = st2[r][2 * q + 1] * __builtin_shufflevector(d.rr[q], d.rr[q], 2, 3) + yacc2;
;                 }
;                 yacc = yacc + yacc2;
.LBB0_75:
	s_waitcnt lgkmcnt(11)
	v_pk_fma_f32 v[138:139], v[88:89], v[130:131], 0 op_sel_hi:[1,1,0]
	v_pk_fma_f32 v[140:141], v[90:91], v[136:137], v[138:139]
	v_pk_fma_f32 v[88:89], v[88:89], v[150:151], 0 op_sel_hi:[1,1,0]
	v_pk_fma_f32 v[90:91], v[90:91], v[152:153], v[88:89]
	s_waitcnt lgkmcnt(10)
	v_pk_fma_f32 v[138:139], v[84:85], v[146:147], v[140:141]
	v_pk_fma_f32 v[140:141], v[86:87], v[148:149], v[138:139]
	v_pk_fma_f32 v[84:85], v[84:85], v[154:155], v[90:91]
	v_pk_fma_f32 v[86:87], v[86:87], v[156:157], v[84:85]
	v_add_f32_e32 v138, v140, v141
	v_add_f32_e32 v84, v86, v87
	s_add_i32 s17, s17, 4
	v_add_f32_dpp v138, v138, v138 quad_perm:[1,0,3,2] row_mask:0xf bank_mask:0xf bound_ctrl:1
	v_add_f32_dpp v84, v84, v84 quad_perm:[1,0,3,2] row_mask:0xf bank_mask:0xf bound_ctrl:1
	v_add_u32_e32 v132, 0x800, v132
	v_add_f32_dpp v138, v138, v138 quad_perm:[2,3,0,1] row_mask:0xf bank_mask:0xf bound_ctrl:1
	v_add_f32_dpp v84, v84, v84 quad_perm:[2,3,0,1] row_mask:0xf bank_mask:0xf bound_ctrl:1
	v_add_u32_e32 v199, 0x1800, v199
	v_add_f32_dpp v160, v138, v138 row_half_mirror row_mask:0xf bank_mask:0xf bound_ctrl:1
	v_add_f32_dpp v84, v84, v84 row_half_mirror row_mask:0xf bank_mask:0xf bound_ctrl:1
	s_waitcnt lgkmcnt(7)
	v_pk_mul_f32 v[138:139], v[76:77], v[160:161] op_sel_hi:[1,0]
	v_pk_mul_f32 v[140:141], v[78:79], v[160:161] op_sel_hi:[1,0]
	v_pk_mul_f32 v[76:77], v[76:77], v[84:85] op_sel_hi:[1,0]
	s_waitcnt lgkmcnt(1)
	v_pk_fma_f32 v[138:139], v[80:81], v[144:145], v[138:139] op_sel_hi:[1,0,1] neg_lo:[0,0,1] neg_hi:[0,0,1]
	v_pk_fma_f32 v[162:163], v[82:83], v[144:145], v[140:141] op_sel_hi:[1,0,1] neg_lo:[0,0,1] neg_hi:[0,0,1]
	v_pk_fma_f32 v[76:77], v[80:81], v[144:145], v[76:77] op_sel:[0,1,0] neg_lo:[0,0,1] neg_hi:[0,0,1]
	v_pk_mul_f32 v[78:79], v[78:79], v[84:85] op_sel_hi:[1,0]
	v_pk_fma_f32 v[140:141], v[56:57], v[130:131], v[138:139]
	v_pk_fma_f32 v[138:139], v[58:59], v[136:137], v[162:163]
	v_pk_mul_f32 v[130:131], v[64:65], v[160:161] op_sel_hi:[1,0]
	v_pk_mul_f32 v[136:137], v[66:67], v[160:161] op_sel_hi:[1,0]
	v_pk_fma_f32 v[78:79], v[82:83], v[144:145], v[78:79] op_sel:[0,1,0] neg_lo:[0,0,1] neg_hi:[0,0,1]
	v_pk_fma_f32 v[76:77], v[56:57], v[150:151], v[76:77]
	v_pk_mul_f32 v[56:57], v[64:65], v[84:85] op_sel_hi:[1,0]
	v_pk_mul_f32 v[64:65], v[66:67], v[84:85] op_sel_hi:[1,0]
	v_pk_fma_f32 v[130:131], v[68:69], v[144:145], v[130:131] op_sel_hi:[1,0,1] neg_lo:[0,0,1] neg_hi:[0,0,1]
	v_pk_fma_f32 v[160:161], v[70:71], v[144:145], v[136:137] op_sel_hi:[1,0,1] neg_lo:[0,0,1] neg_hi:[0,0,1]
	v_pk_fma_f32 v[58:59], v[58:59], v[152:153], v[78:79]
	v_pk_fma_f32 v[56:57], v[68:69], v[144:145], v[56:57] op_sel:[0,1,0] neg_lo:[0,0,1] neg_hi:[0,0,1]
	v_pk_fma_f32 v[64:65], v[70:71], v[144:145], v[64:65] op_sel:[0,1,0] neg_lo:[0,0,1] neg_hi:[0,0,1]
	v_pk_fma_f32 v[162:163], v[72:73], v[140:141], 0 op_sel_hi:[1,1,0]
	v_pk_fma_f32 v[168:169], v[74:75], v[138:139], v[162:163]
	v_pk_fma_f32 v[136:137], v[52:53], v[146:147], v[130:131]
	v_pk_fma_f32 v[130:131], v[54:55], v[148:149], v[160:161]
	v_pk_fma_f32 v[72:73], v[72:73], v[76:77], 0 op_sel_hi:[1,1,0]
	v_pk_fma_f32 v[74:75], v[74:75], v[58:59], v[72:73]
	v_pk_fma_f32 v[56:57], v[52:53], v[154:155], v[56:57]
	v_pk_fma_f32 v[52:53], v[54:55], v[156:157], v[64:65]
	v_pk_fma_f32 v[146:147], v[60:61], v[136:137], v[168:169]
	v_pk_fma_f32 v[148:149], v[62:63], v[130:131], v[146:147]
	v_pk_fma_f32 v[54:55], v[60:61], v[56:57], v[74:75]
	v_pk_fma_f32 v[60:61], v[62:63], v[52:53], v[54:55]
	v_add_f32_e32 v146, v148, v149
	v_add_f32_e32 v54, v60, v61
	v_add_u32_e32 v200, 0x1800, v200
	v_add_f32_dpp v146, v146, v146 quad_perm:[1,0,3,2] row_mask:0xf bank_mask:0xf bound_ctrl:1
	v_add_f32_dpp v54, v54, v54 quad_perm:[1,0,3,2] row_mask:0xf bank_mask:0xf bound_ctrl:1
	s_and_b64 vcc, exec, s[30:31]
	v_add_f32_dpp v146, v146, v146 quad_perm:[2,3,0,1] row_mask:0xf bank_mask:0xf bound_ctrl:1
	v_add_f32_dpp v54, v54, v54 quad_perm:[2,3,0,1] row_mask:0xf bank_mask:0xf bound_ctrl:1
	ds_write2_b32 v201, v146, v54 offset0:128 offset1:130
	s_cbranch_vccnz .LBB0_78
.LBB0_76:
	s_waitcnt lgkmcnt(10)
	v_pk_fma_f32 v[90:91], v[140:141], v[20:21], 0 op_sel_hi:[1,1,0]
	v_pk_fma_f32 v[156:157], v[138:139], v[22:23], v[90:91]
	v_pk_fma_f32 v[20:21], v[76:77], v[20:21], 0 op_sel_hi:[1,1,0]
	v_pk_fma_f32 v[22:23], v[58:59], v[22:23], v[20:21]
	s_waitcnt lgkmcnt(9)
	v_pk_fma_f32 v[20:21], v[56:57], v[24:25], v[22:23]
	v_pk_fma_f32 v[22:23], v[52:53], v[26:27], v[20:21]
	v_pk_fma_f32 v[90:91], v[136:137], v[24:25], v[156:157]
	v_pk_fma_f32 v[156:157], v[130:131], v[26:27], v[90:91]
	v_add_f32_e32 v20, v22, v23
	v_add_f32_e32 v90, v156, v157
	ds_read_b128 v[60:63], v200
	ds_read_b128 v[64:67], v200 offset:16
	ds_read_b128 v[68:71], v200 offset:256
	ds_read_b128 v[72:75], v200 offset:272
	ds_read_b128 v[78:81], v200 offset:512
	ds_read_b128 v[82:85], v200 offset:528
	ds_read_b128 v[86:89], v200 offset:768
	ds_read_b128 v[144:147], v200 offset:784
	ds_read_b128 v[148:151], v200 offset:1024
	ds_read_b128 v[152:155], v200 offset:1040
	ds_read_b64 v[54:55], v199
	v_add_f32_dpp v20, v20, v20 quad_perm:[1,0,3,2] row_mask:0xf bank_mask:0xf bound_ctrl:1
	v_add_f32_dpp v90, v90, v90 quad_perm:[1,0,3,2] row_mask:0xf bank_mask:0xf bound_ctrl:1
	s_cmp_gt_u32 s17, 11
	v_add_f32_dpp v20, v20, v20 quad_perm:[2,3,0,1] row_mask:0xf bank_mask:0xf bound_ctrl:1
	v_add_f32_dpp v90, v90, v90 quad_perm:[2,3,0,1] row_mask:0xf bank_mask:0xf bound_ctrl:1
	s_cselect_b64 s[30:31], -1, 0
	v_add_f32_dpp v20, v20, v20 row_half_mirror row_mask:0xf bank_mask:0xf bound_ctrl:1
	v_add_f32_dpp v90, v90, v90 row_half_mirror row_mask:0xf bank_mask:0xf bound_ctrl:1
	s_waitcnt lgkmcnt(14)
; __device__ __forceinline__ float red4(float v) { v += dppf<0xB1>(v); v += dppf<0x4E>(v); return v; }
; __device__ __forceinline__ float red8(float v) { v = red4(v); v += dppf<0x141>(v); return v; }
; template <int R, int DEFY> __forceinline__
; __device__ __forceinline__ void scan_chain(const Params& p, int j, int seq_start, int len, int h, int dir, int gtid, float* lds  , bool do_steps, bool do_prep, int row_base, int nrows) {
;     ...
;         auto cstep = [&](int s, const VS& d) {
;             float yo[R];
; #pragma unroll
;             for (int r = 0; r < R; ++r) {
;                 f2 sacc = {0.f, 0.f}, sacc2 = {0.f, 0.f};
; #pragma unroll
;                 for (int q = 0; q < NQ; ++q) {
;                     sacc = st2[r][2 * q] * __builtin_shufflevector(d.kk[q], d.kk[q], 0, 1) + sacc;
;                     sacc2 = st2[r][2 * q + 1] * __builtin_shufflevector(d.kk[q], d.kk[q], 2, 3) + sacc2;
;                 }
;                 sacc = sacc + sacc2;
;                 float sa = sacc.x + sacc.y;
;                 sa = red8(sa);
;                 const f2 sa2 = {sa, sa}, v2 = {d.vv[r], d.vv[r]};
;                 f2 yacc = {0.f, 0.f}, yacc2 = {0.f, 0.f};
; #pragma unroll
;                 for (int q = 0; q < NQ; ++q) {
;                     const f2 t0 = v2 * __builtin_shufflevector(d.kd[q], d.kd[q], 0, 1) - sa2 * __builtin_shufflevector(d.ka[q], d.ka[q], 0, 1);
;                     const f2 t1 = v2 * __builtin_shufflevector(d.kd[q], d.kd[q], 2, 3) - sa2 * __builtin_shufflevector(d.ka[q], d.ka[q], 2, 3);
;                     st2[r][2 * q] = st2[r][2 * q] * __builtin_shufflevector(d.w[q], d.w[q], 0, 1) + t0;
;                     st2[r][2 * q + 1] = st2[r][2 * q + 1] * __builtin_shufflevector(d.w[q], d.w[q], 2, 3) + t1;
;                     yacc = st2[r][2 * q] * __builtin_shufflevector(d.rr[q], d.rr[q], 0, 1) + yacc;
;                     yacc2 = st2[r][2 * q + 1] * __builtin_shufflevector(d.rr[q], d.rr[q], 2, 3) + yacc2;
;                 }
;                 yacc = yacc + yacc2;
;                 yo[r] = (DEFY == 1) ? (yacc.x + yacc.y) : ((DEFY == 2) ? red4(yacc.x + yacc.y) : red8(yacc.x + yacc.y));
;             }
	v_pk_mul_f32 v[22:23], v[32:33], v[20:21] op_sel_hi:[1,0]
	v_pk_mul_f32 v[156:157], v[32:33], v[90:91] op_sel_hi:[1,0]
	v_pk_mul_f32 v[160:161], v[34:35], v[90:91] op_sel_hi:[1,0]
	s_waitcnt lgkmcnt(11)
	v_pk_fma_f32 v[22:23], v[44:45], v[142:143], v[22:23] op_sel:[0,1,0] neg_lo:[0,0,1] neg_hi:[0,0,1]
	v_pk_mul_f32 v[24:25], v[34:35], v[20:21] op_sel_hi:[1,0]
	v_pk_fma_f32 v[156:157], v[44:45], v[142:143], v[156:157] op_sel_hi:[1,0,1] neg_lo:[0,0,1] neg_hi:[0,0,1]
	v_pk_fma_f32 v[160:161], v[46:47], v[142:143], v[160:161] op_sel_hi:[1,0,1] neg_lo:[0,0,1] neg_hi:[0,0,1]
	v_pk_mul_f32 v[162:163], v[28:29], v[90:91] op_sel_hi:[1,0]
	v_pk_mul_f32 v[90:91], v[30:31], v[90:91] op_sel_hi:[1,0]
	v_pk_fma_f32 v[24:25], v[46:47], v[142:143], v[24:25] op_sel:[0,1,0] neg_lo:[0,0,1] neg_hi:[0,0,1]
	v_pk_fma_f32 v[76:77], v[76:77], v[12:13], v[22:23]
	v_pk_mul_f32 v[22:23], v[28:29], v[20:21] op_sel_hi:[1,0]
	v_pk_mul_f32 v[20:21], v[30:31], v[20:21] op_sel_hi:[1,0]
	v_pk_fma_f32 v[140:141], v[140:141], v[12:13], v[156:157]
	v_pk_fma_f32 v[138:139], v[138:139], v[14:15], v[160:161]
	v_pk_fma_f32 v[162:163], v[36:37], v[142:143], v[162:163] op_sel_hi:[1,0,1] neg_lo:[0,0,1] neg_hi:[0,0,1]
	v_pk_fma_f32 v[90:91], v[38:39], v[142:143], v[90:91] op_sel_hi:[1,0,1] neg_lo:[0,0,1] neg_hi:[0,0,1]
	v_pk_fma_f32 v[58:59], v[58:59], v[14:15], v[24:25]
	v_pk_fma_f32 v[22:23], v[36:37], v[142:143], v[22:23] op_sel:[0,1,0] neg_lo:[0,0,1] neg_hi:[0,0,1]
	v_pk_fma_f32 v[20:21], v[38:39], v[142:143], v[20:21] op_sel:[0,1,0] neg_lo:[0,0,1] neg_hi:[0,0,1]
	v_pk_fma_f32 v[156:157], v[48:49], v[140:141], 0 op_sel_hi:[1,1,0]
	v_pk_fma_f32 v[160:161], v[50:51], v[138:139], v[156:157]
	v_pk_fma_f32 v[136:137], v[136:137], v[16:17], v[162:163]
	v_pk_fma_f32 v[90:91], v[130:131], v[18:19], v[90:91]
	v_pk_fma_f32 v[12:13], v[48:49], v[76:77], 0 op_sel_hi:[1,1,0]
	v_pk_fma_f32 v[14:15], v[50:51], v[58:59], v[12:13]
	v_pk_fma_f32 v[56:57], v[56:57], v[16:17], v[22:23]
	v_pk_fma_f32 v[52:53], v[52:53], v[18:19], v[20:21]
	v_pk_fma_f32 v[130:131], v[40:41], v[136:137], v[160:161]
	v_pk_fma_f32 v[156:157], v[42:43], v[90:91], v[130:131]
	v_pk_fma_f32 v[12:13], v[40:41], v[56:57], v[14:15]
	v_pk_fma_f32 v[14:15], v[42:43], v[52:53], v[12:13]
	v_add_f32_e32 v130, v156, v157
	v_add_f32_e32 v12, v14, v15
	s_waitcnt lgkmcnt(10)
	v_pk_fma_f32 v[156:157], v[62:63], v[138:139], 0 op_sel_hi:[1,1,0]
	v_add_f32_dpp v130, v130, v130 quad_perm:[1,0,3,2] row_mask:0xf bank_mask:0xf bound_ctrl:1
	v_add_f32_dpp v12, v12, v12 quad_perm:[1,0,3,2] row_mask:0xf bank_mask:0xf bound_ctrl:1
	s_waitcnt lgkmcnt(9)
	v_pk_fma_f32 v[156:157], v[66:67], v[90:91], v[156:157]
	v_add_f32_dpp v130, v130, v130 quad_perm:[2,3,0,1] row_mask:0xf bank_mask:0xf bound_ctrl:1
	v_add_f32_dpp v12, v12, v12 quad_perm:[2,3,0,1] row_mask:0xf bank_mask:0xf bound_ctrl:1
	ds_write2_b32 v132, v130, v12 offset1:2
	v_pk_fma_f32 v[130:131], v[60:61], v[140:141], v[156:157]
	v_pk_fma_f32 v[60:61], v[60:61], v[76:77], 0 op_sel_hi:[1,1,0]
	v_pk_fma_f32 v[130:131], v[64:65], v[136:137], v[130:131]
	v_pk_fma_f32 v[62:63], v[62:63], v[58:59], v[60:61]
	v_pk_fma_f32 v[60:61], v[64:65], v[56:57], v[62:63]
	v_add_f32_e32 v130, v130, v131
	v_pk_fma_f32 v[62:63], v[66:67], v[52:53], v[60:61]
	ds_read_b128 v[20:23], v200 offset:1536
	ds_read_b128 v[24:27], v200 offset:1552
	ds_read_b128 v[12:15], v200 offset:1792
	ds_read_b128 v[16:19], v200 offset:1808
	ds_read_b128 v[32:35], v200 offset:2048
	ds_read_b128 v[28:31], v200 offset:2064
	ds_read_b128 v[44:47], v200 offset:2304
	ds_read_b128 v[36:39], v200 offset:2320
	ds_read_b128 v[48:51], v200 offset:2560
	ds_read_b128 v[40:43], v200 offset:2576
	ds_read_b64 v[142:143], v199 offset:1536
	v_add_f32_dpp v130, v130, v130 quad_perm:[1,0,3,2] row_mask:0xf bank_mask:0xf bound_ctrl:1
	v_add_u32_e32 v201, 0x400, v132
	v_add_f32_dpp v130, v130, v130 quad_perm:[2,3,0,1] row_mask:0xf bank_mask:0xf bound_ctrl:1
	v_add_f32_e32 v60, v62, v63
	s_and_b64 vcc, exec, s[30:31]
	v_add_f32_dpp v130, v130, v130 row_half_mirror row_mask:0xf bank_mask:0xf bound_ctrl:1
	s_waitcnt lgkmcnt(14)
	v_pk_mul_f32 v[156:157], v[78:79], v[130:131] op_sel_hi:[1,0]
	v_pk_mul_f32 v[160:161], v[80:81], v[130:131] op_sel_hi:[1,0]
	s_waitcnt lgkmcnt(12)
	v_pk_fma_f32 v[156:157], v[86:87], v[54:55], v[156:157] op_sel_hi:[1,0,1] neg_lo:[0,0,1] neg_hi:[0,0,1]
	v_pk_fma_f32 v[160:161], v[88:89], v[54:55], v[160:161] op_sel_hi:[1,0,1] neg_lo:[0,0,1] neg_hi:[0,0,1]
	v_pk_mul_f32 v[162:163], v[82:83], v[130:131] op_sel_hi:[1,0]
	v_pk_mul_f32 v[130:131], v[84:85], v[130:131] op_sel_hi:[1,0]
	v_pk_fma_f32 v[140:141], v[68:69], v[140:141], v[156:157]
	v_pk_fma_f32 v[138:139], v[70:71], v[138:139], v[160:161]
	v_pk_fma_f32 v[162:163], v[144:145], v[54:55], v[162:163] op_sel_hi:[1,0,1] neg_lo:[0,0,1] neg_hi:[0,0,1]
	v_pk_fma_f32 v[130:131], v[146:147], v[54:55], v[130:131] op_sel_hi:[1,0,1] neg_lo:[0,0,1] neg_hi:[0,0,1]
	v_pk_fma_f32 v[156:157], v[148:149], v[140:141], 0 op_sel_hi:[1,1,0]
	v_pk_fma_f32 v[160:161], v[150:151], v[138:139], 0 op_sel_hi:[1,1,0]
	v_pk_fma_f32 v[162:163], v[72:73], v[136:137], v[162:163]
	v_pk_fma_f32 v[168:169], v[74:75], v[90:91], v[130:131]
	v_pk_fma_f32 v[90:91], v[152:153], v[162:163], v[156:157]
	v_pk_fma_f32 v[130:131], v[154:155], v[168:169], v[160:161]
	v_add_f32_dpp v60, v60, v60 quad_perm:[1,0,3,2] row_mask:0xf bank_mask:0xf bound_ctrl:1
	v_pk_add_f32 v[90:91], v[90:91], v[130:131]
	s_waitcnt lgkmcnt(10)
	v_pk_fma_f32 v[130:131], v[20:21], v[140:141], 0 op_sel_hi:[1,1,0]
	v_pk_fma_f32 v[136:137], v[22:23], v[138:139], v[130:131]
	v_add_f32_dpp v60, v60, v60 quad_perm:[2,3,0,1] row_mask:0xf bank_mask:0xf bound_ctrl:1
	s_waitcnt lgkmcnt(9)
; template <int R, int DEFY> __forceinline__
; __device__ __forceinline__ void scan_chain(const Params& p, int j, int seq_start, int len, int h, int dir, int gtid, float* lds  , bool do_steps, bool do_prep, int row_base, int nrows) {
;     ...
;         auto cstep = [&](int s, const VS& d) {
;             float yo[R];
; #pragma unroll
;             for (int r = 0; r < R; ++r) {
;                 f2 sacc = {0.f, 0.f}, sacc2 = {0.f, 0.f};
; #pragma unroll
;                 for (int q = 0; q < NQ; ++q) {
;                     sacc = st2[r][2 * q] * __builtin_shufflevector(d.kk[q], d.kk[q], 0, 1) + sacc;
;                     sacc2 = st2[r][2 * q + 1] * __builtin_shufflevector(d.kk[q], d.kk[q], 2, 3) + sacc2;
;                 }
;                 sacc = sacc + sacc2;
;                 float sa = sacc.x + sacc.y;
;                 sa = red8(sa);
;                 const f2 sa2 = {sa, sa}, v2 = {d.vv[r], d.vv[r]};
;                 f2 yacc = {0.f, 0.f}, yacc2 = {0.f, 0.f};
; #pragma unroll
;                 for (int q = 0; q < NQ; ++q) {
;                     const f2 t0 = v2 * __builtin_shufflevector(d.kd[q], d.kd[q], 0, 1) - sa2 * __builtin_shufflevector(d.ka[q], d.ka[q], 0, 1);
;                     const f2 t1 = v2 * __builtin_shufflevector(d.kd[q], d.kd[q], 2, 3) - sa2 * __builtin_shufflevector(d.ka[q], d.ka[q], 2, 3);
;                     st2[r][2 * q] = st2[r][2 * q] * __builtin_shufflevector(d.w[q], d.w[q], 0, 1) + t0;
;                     st2[r][2 * q + 1] = st2[r][2 * q + 1] * __builtin_shufflevector(d.w[q], d.w[q], 2, 3) + t1;
;                     yacc = st2[r][2 * q] * __builtin_shufflevector(d.rr[q], d.rr[q], 0, 1) + yacc;
;                     yacc2 = st2[r][2 * q + 1] * __builtin_shufflevector(d.rr[q], d.rr[q], 2, 3) + yacc2;
;                 }
;                 yacc = yacc + yacc2;
;                 yo[r] = (DEFY == 1) ? (yacc.x + yacc.y) : ((DEFY == 2) ? red4(yacc.x + yacc.y) : red8(yacc.x + yacc.y));
;             }
;             if (DEFY == 1) {
; #pragma unroll
;                 for (int r = 0; r < R; ++r) ys[(s * 64 + row + r) * 8 + seg] = yo[r];
;             } else if (DEFY == 2) {
; #pragma unroll
;                 for (int r = 0; r < R; ++r) ys[(s * 64 + row + r) * 2 + (seg >> 2)] = yo[r];
;             } else {
; #pragma unroll
;                 for (int r = 0; r < R; ++r) ys[s * 64 + row + r] = yo[r];
;             }
	v_pk_fma_f32 v[130:131], v[24:25], v[162:163], v[136:137]
	v_pk_fma_f32 v[136:137], v[26:27], v[168:169], v[130:131]
	v_add_f32_dpp v60, v60, v60 row_half_mirror row_mask:0xf bank_mask:0xf bound_ctrl:1
	v_pk_mul_f32 v[64:65], v[80:81], v[60:61] op_sel_hi:[1,0]
	v_add_f32_e32 v130, v136, v137
	v_pk_fma_f32 v[64:65], v[88:89], v[54:55], v[64:65] op_sel:[0,1,0] neg_lo:[0,0,1] neg_hi:[0,0,1]
	v_pk_mul_f32 v[62:63], v[78:79], v[60:61] op_sel_hi:[1,0]
	v_add_f32_dpp v130, v130, v130 quad_perm:[1,0,3,2] row_mask:0xf bank_mask:0xf bound_ctrl:1
	v_pk_fma_f32 v[160:161], v[70:71], v[58:59], v[64:65]
	v_pk_mul_f32 v[64:65], v[82:83], v[60:61] op_sel_hi:[1,0]
	v_pk_mul_f32 v[60:61], v[84:85], v[60:61] op_sel_hi:[1,0]
	v_add_f32_dpp v130, v130, v130 quad_perm:[2,3,0,1] row_mask:0xf bank_mask:0xf bound_ctrl:1
	v_pk_fma_f32 v[62:63], v[86:87], v[54:55], v[62:63] op_sel:[0,1,0] neg_lo:[0,0,1] neg_hi:[0,0,1]
	v_pk_fma_f32 v[64:65], v[144:145], v[54:55], v[64:65] op_sel:[0,1,0] neg_lo:[0,0,1] neg_hi:[0,0,1]
	v_pk_fma_f32 v[54:55], v[146:147], v[54:55], v[60:61] op_sel:[0,1,0] neg_lo:[0,0,1] neg_hi:[0,0,1]
	v_add_f32_dpp v146, v130, v130 row_half_mirror row_mask:0xf bank_mask:0xf bound_ctrl:1
	v_pk_fma_f32 v[156:157], v[68:69], v[76:77], v[62:63]
	s_waitcnt lgkmcnt(6)
	v_pk_mul_f32 v[130:131], v[32:33], v[146:147] op_sel_hi:[1,0]
	v_pk_mul_f32 v[136:137], v[34:35], v[146:147] op_sel_hi:[1,0]
	v_pk_fma_f32 v[58:59], v[148:149], v[156:157], 0 op_sel_hi:[1,1,0]
	s_waitcnt lgkmcnt(0)
	v_pk_fma_f32 v[130:131], v[44:45], v[142:143], v[130:131] op_sel_hi:[1,0,1] neg_lo:[0,0,1] neg_hi:[0,0,1]
	v_pk_fma_f32 v[136:137], v[46:47], v[142:143], v[136:137] op_sel_hi:[1,0,1] neg_lo:[0,0,1] neg_hi:[0,0,1]
	v_pk_mul_f32 v[148:149], v[28:29], v[146:147] op_sel_hi:[1,0]
	v_pk_mul_f32 v[146:147], v[30:31], v[146:147] op_sel_hi:[1,0]
	v_pk_fma_f32 v[62:63], v[150:151], v[160:161], v[58:59]
	v_pk_fma_f32 v[130:131], v[12:13], v[140:141], v[130:131]
	v_pk_fma_f32 v[136:137], v[14:15], v[138:139], v[136:137]
	v_pk_fma_f32 v[148:149], v[36:37], v[142:143], v[148:149] op_sel_hi:[1,0,1] neg_lo:[0,0,1] neg_hi:[0,0,1]
	v_pk_fma_f32 v[150:151], v[38:39], v[142:143], v[146:147] op_sel_hi:[1,0,1] neg_lo:[0,0,1] neg_hi:[0,0,1]
	v_pk_fma_f32 v[202:203], v[72:73], v[56:57], v[64:65]
	v_pk_fma_f32 v[204:205], v[74:75], v[52:53], v[54:55]
	v_pk_fma_f32 v[138:139], v[48:49], v[130:131], 0 op_sel_hi:[1,1,0]
	v_pk_fma_f32 v[140:141], v[50:51], v[136:137], v[138:139]
	v_pk_fma_f32 v[146:147], v[16:17], v[162:163], v[148:149]
	v_pk_fma_f32 v[148:149], v[18:19], v[168:169], v[150:151]
	v_pk_fma_f32 v[52:53], v[152:153], v[202:203], v[62:63]
	v_pk_fma_f32 v[54:55], v[154:155], v[204:205], v[52:53]
	v_pk_fma_f32 v[138:139], v[40:41], v[146:147], v[140:141]
	v_pk_fma_f32 v[140:141], v[42:43], v[148:149], v[138:139]
	v_add_f32_e32 v90, v90, v91
	v_add_f32_e32 v52, v54, v55
	v_add_f32_e32 v138, v140, v141
	v_add_f32_dpp v90, v90, v90 quad_perm:[1,0,3,2] row_mask:0xf bank_mask:0xf bound_ctrl:1
	v_add_f32_dpp v52, v52, v52 quad_perm:[1,0,3,2] row_mask:0xf bank_mask:0xf bound_ctrl:1
	v_add_f32_dpp v138, v138, v138 quad_perm:[1,0,3,2] row_mask:0xf bank_mask:0xf bound_ctrl:1
	v_add_f32_dpp v90, v90, v90 quad_perm:[2,3,0,1] row_mask:0xf bank_mask:0xf bound_ctrl:1
	v_add_f32_dpp v52, v52, v52 quad_perm:[2,3,0,1] row_mask:0xf bank_mask:0xf bound_ctrl:1
	v_add_f32_dpp v162, v138, v138 quad_perm:[2,3,0,1] row_mask:0xf bank_mask:0xf bound_ctrl:1
	v_pk_fma_f32 v[138:139], v[20:21], v[156:157], 0 op_sel_hi:[1,1,0]
	v_pk_fma_f32 v[140:141], v[22:23], v[160:161], v[138:139]
	ds_write2_b32 v132, v90, v52 offset0:128 offset1:130
	v_pk_fma_f32 v[138:139], v[24:25], v[202:203], v[140:141]
	v_pk_fma_f32 v[140:141], v[26:27], v[204:205], v[138:139]
	ds_read_b128 v[88:91], v200 offset:3072
	ds_read_b128 v[84:87], v200 offset:3088
	ds_read_b128 v[56:59], v200 offset:3328
	ds_read_b128 v[52:55], v200 offset:3344
	ds_read_b128 v[76:79], v200 offset:3584
	ds_read_b128 v[64:67], v200 offset:3600
	ds_read_b128 v[80:83], v200 offset:3840
	ds_read_b128 v[68:71], v200 offset:3856
	ds_read_b128 v[72:75], v200 offset:4096
	ds_read_b128 v[60:63], v200 offset:4112
	ds_read_b64 v[144:145], v199 offset:3072
	s_nop 0
	v_add_f32_e32 v138, v140, v141
	s_nop 1
	v_add_f32_dpp v138, v138, v138 quad_perm:[1,0,3,2] row_mask:0xf bank_mask:0xf bound_ctrl:1
	s_nop 1
	v_add_f32_dpp v138, v138, v138 quad_perm:[2,3,0,1] row_mask:0xf bank_mask:0xf bound_ctrl:1
	s_nop 1
	v_add_f32_dpp v138, v138, v138 row_half_mirror row_mask:0xf bank_mask:0xf bound_ctrl:1
	v_pk_mul_f32 v[140:141], v[32:33], v[138:139] op_sel_hi:[1,0]
	v_pk_mul_f32 v[150:151], v[34:35], v[138:139] op_sel_hi:[1,0]
	v_pk_fma_f32 v[140:141], v[44:45], v[142:143], v[140:141] op_sel:[0,1,0] neg_lo:[0,0,1] neg_hi:[0,0,1]
	v_pk_fma_f32 v[152:153], v[46:47], v[142:143], v[150:151] op_sel:[0,1,0] neg_lo:[0,0,1] neg_hi:[0,0,1]
	v_pk_mul_f32 v[154:155], v[28:29], v[138:139] op_sel_hi:[1,0]
	v_pk_mul_f32 v[138:139], v[30:31], v[138:139] op_sel_hi:[1,0]
	v_pk_fma_f32 v[150:151], v[12:13], v[156:157], v[140:141]
	v_pk_fma_f32 v[152:153], v[14:15], v[160:161], v[152:153]
	v_pk_fma_f32 v[154:155], v[36:37], v[142:143], v[154:155] op_sel:[0,1,0] neg_lo:[0,0,1] neg_hi:[0,0,1]
	v_pk_fma_f32 v[138:139], v[38:39], v[142:143], v[138:139] op_sel:[0,1,0] neg_lo:[0,0,1] neg_hi:[0,0,1]
	v_pk_fma_f32 v[140:141], v[48:49], v[150:151], 0 op_sel_hi:[1,1,0]
	v_pk_fma_f32 v[160:161], v[50:51], v[152:153], v[140:141]
	v_pk_fma_f32 v[154:155], v[16:17], v[202:203], v[154:155]
	v_pk_fma_f32 v[156:157], v[18:19], v[204:205], v[138:139]
	v_pk_fma_f32 v[138:139], v[40:41], v[154:155], v[160:161]
	v_pk_fma_f32 v[140:141], v[42:43], v[156:157], v[138:139]
	s_nop 0
	s_nop 0
	v_add_f32_e32 v138, v140, v141
	s_nop 1
	v_add_f32_dpp v138, v138, v138 quad_perm:[1,0,3,2] row_mask:0xf bank_mask:0xf bound_ctrl:1
	s_nop 1
	v_add_f32_dpp v138, v138, v138 quad_perm:[2,3,0,1] row_mask:0xf bank_mask:0xf bound_ctrl:1
	ds_write2_b32 v201, v162, v138 offset1:2
	s_cbranch_vccnz .LBB0_75
	ds_read_b128 v[20:23], v200 offset:4608
	ds_read_b128 v[24:27], v200 offset:4624
	ds_read_b128 v[12:15], v200 offset:4864
	ds_read_b128 v[16:19], v200 offset:4880
	ds_read_b128 v[32:35], v200 offset:5120
	ds_read_b128 v[28:31], v200 offset:5136
	ds_read_b128 v[44:47], v200 offset:5376
	ds_read_b128 v[36:39], v200 offset:5392
	ds_read_b128 v[48:51], v200 offset:5632
	ds_read_b128 v[40:43], v200 offset:5648
	ds_read_b64 v[142:143], v199 offset:4608
	s_branch .LBB0_75
